# attnA: constant-bias tiles (keys beyond the clip distance) initialised with eight 16-byte LDS reads of a replicated constant instead of one read plus 31 register moves
# baseline (speedup 1.0000x reference)
; #define LAS __attribute__((address_space(3)))
; #define WG_BARRIER() do { asm volatile("s_waitcnt vmcnt(0) lgkmcnt(0)" ::: "memory"); __builtin_amdgcn_s_barrier(); asm volatile("" ::: "memory"); } while (0)
; __device__ __forceinline__ void blk_unit_of(int u, int& bh, int& ub) { bh = u >> 4; ub = u & 15; if ((u >> 8) & 1) ub = 15 - ub; }
; template <bool FIXED> __device__ __forceinline__ void attnA_blk(const bf16* Q, const bf16* K, const bf16* Vt, bf16* O, const float* rel_bias, float ref, LAS unsigned char* lds, int vcu, int G, int tid) {
;     ...
;     for (int i = tid; i < 16 * 513; i += NTHREADS) biasL[(i / 513) * 516 + (i % 513)] = rel_bias[i] * LOG2E - (FIXED ? ref : 0.f);
;     __syncthreads();
;     const int lane = tid & 63, r32 = lane & 31, hi = lane >> 5, wid = __builtin_amdgcn_readfirstlane(tid >> 6);
; #pragma unroll 1
;     for (int u = vcu; u < NB * NH * 16; u += G) {
;         int bh, ub; blk_unit_of(u, bh, ub); const int b = bh >> 4, h = bh & 15, qb = ub * 8 + wid, c = qb >> 1, qh = qb & 1;
;         const size_t qrow = (size_t)b * SEQ + qb * 32 + r32;
;         bf16x8 qr[4]; load_q(qr, Q, qrow, h, hi);
;         f32x16 o0 = (f32x16){}, o1 = (f32x16){}; float m = -1e30f, l = 0.f;
;         const LAS float* bl = biasL + h * 516;
;         const bf16* Kh = K + h * HD; const bf16* Vth = Vt + (size_t)h * HD * VTP;
;         const int c0 = ub * 4, t_lo = c0 >= 8 ? c0 - 8 : 0, t_hi = c0 + 3;
;         const size_t kbase = (size_t)b * SEQ; const int ntl = t_hi - t_lo + 1;
;         KVStage sa, sb;
;         kv_issue(sa, Kh, Vth, kbase + (size_t)t_lo * 64, tid); kv_issue(sb, Kh, Vth, kbase + (size_t)(t_lo + 1) * 64, tid);
;         kv_write(sa, lds, tid); kv_write(sb, lds + KVBUF_B, tid); WG_BARRIER();
.LBB0_482:
	s_or_b64 exec, exec, s[16:17]
	v_readlane_b32 s0, v248, 29
	v_readlane_b32 s1, v248, 30
	s_andn2_b64 vcc, exec, s[0:1]
	v_readfirstlane_b32 s0, v98
	s_waitcnt lgkmcnt(0)
	s_barrier
	s_cbranch_vccnz .LBB0_515
	v_cmp_gt_u32_e32 vcc, 16, v98
	s_and_saveexec_b64 s[98:99], vcc
	v_mul_u32_u24_e32 v2, 0x810, v98
	v_add_u32_e32 v2, 0x12800, v2
	ds_read_b32 v3, v2
	s_waitcnt lgkmcnt(0)
	ds_write_b32 v2, v3 offset:4
	ds_write_b32 v2, v3 offset:8
	ds_write_b32 v2, v3 offset:12
	s_mov_b64 exec, s[98:99]
	s_ashr_i32 s16, s0, 6
	s_add_u32 s0, s94, s14
	s_addc_u32 s1, s95, s15
	s_add_u32 s0, s0, 0xea00000
	s_addc_u32 s1, s1, 0
	s_add_u32 s12, s94, s12
	s_addc_u32 s13, s95, s13
	s_add_u32 s17, s12, 0x12a00000
	s_addc_u32 s18, s13, 0
	s_add_u32 s10, s94, s10
	s_addc_u32 s11, s95, s11
	s_add_u32 s6, s94, s8
	v_ashrrev_i32_e32 v116, 3, v98
	v_mov_b64_e32 v[2:3], s[10:11]
	s_mov_b32 s8, 0x11100
	s_addc_u32 s7, s95, s9
	v_mad_i64_i32 v[118:119], s[8:9], v116, s8, v[2:3]
	s_mov_b64 s[8:9], 0x16a00000
	s_add_u32 s6, s6, 0xaa00000
	v_lshl_add_u64 v[120:121], v[118:119], 0, s[8:9]
	s_movk_i32 s8, 0x90
	s_addc_u32 s7, s7, 0
	v_and_b32_e32 v112, 31, v98
	v_mul_lo_u32 v2, v116, s8
	v_lshlrev_b32_e32 v3, 4, v98
	s_lshl_b32 s8, s16, 5
	v_bfe_u32 v6, v98, 5, 1
	v_and_b32_e32 v3, 0x70, v3
	v_and_or_b32 v115, s8, 32, v112
	v_lshlrev_b32_e32 v4, 1, v98
	v_lshrrev_b32_e32 v5, 1, v98
	v_lshlrev_b32_e32 v114, 3, v6
	v_add3_u32 v113, 0, v2, v3
	v_or_b32_e32 v3, 0x100, v115
	v_and_b32_e32 v2, 19, v98
	v_and_b32_e32 v4, 8, v4
	v_and_b32_e32 v5, 4, v5
	v_or3_b32 v2, v5, v2, v4
	v_sub_u32_e32 v4, v3, v114
	v_min_u32_e32 v140, 0x100, v4
	v_min_u32_e32 v141, 0x120, v4
	v_xad_u32 v4, v114, -1, v3
	v_min_u32_e32 v142, 0x100, v4
	v_min_u32_e32 v143, 0x120, v4
	v_or_b32_e32 v4, 2, v114
	v_sub_u32_e32 v4, v3, v4
	v_min_u32_e32 v144, 0x100, v4
	v_min_u32_e32 v145, 0x120, v4
	v_or_b32_e32 v4, 3, v114
	v_sub_u32_e32 v4, v3, v4
	v_min_u32_e32 v146, 0x100, v4
	v_min_u32_e32 v147, 0x120, v4
	v_or_b32_e32 v4, 4, v114
	v_sub_u32_e32 v4, v3, v4
	v_min_u32_e32 v148, 0x100, v4
	v_min_u32_e32 v149, 0x120, v4
	v_or_b32_e32 v4, 5, v114
	v_sub_u32_e32 v4, v3, v4
	v_min_u32_e32 v150, 0x100, v4
	v_min_u32_e32 v151, 0x120, v4
	v_or_b32_e32 v4, 6, v114
	v_sub_u32_e32 v4, v3, v4
	v_min_u32_e32 v152, 0x100, v4
	v_min_u32_e32 v153, 0x120, v4
	v_or_b32_e32 v4, 7, v114
	v_sub_u32_e32 v4, v3, v4
	v_min_u32_e32 v154, 0x100, v4
	v_min_u32_e32 v155, 0x120, v4
	v_or_b32_e32 v4, 16, v114
	v_sub_u32_e32 v4, v3, v4
	v_min_u32_e32 v156, 0x100, v4
	v_min_u32_e32 v157, 0x120, v4
	v_or_b32_e32 v4, 17, v114
	v_sub_u32_e32 v4, v3, v4
	v_min_u32_e32 v158, 0x100, v4
	v_min_u32_e32 v159, 0x120, v4
	v_or_b32_e32 v4, 18, v114
	v_sub_u32_e32 v4, v3, v4
	v_min_u32_e32 v160, 0x100, v4
	v_min_u32_e32 v161, 0x120, v4
	v_or_b32_e32 v4, 19, v114
	v_sub_u32_e32 v4, v3, v4
	v_min_u32_e32 v162, 0x100, v4
	v_min_u32_e32 v163, 0x120, v4
	v_or_b32_e32 v4, 20, v114
	v_sub_u32_e32 v4, v3, v4
	v_min_u32_e32 v164, 0x100, v4
	v_min_u32_e32 v165, 0x120, v4
	v_or_b32_e32 v4, 21, v114
	v_sub_u32_e32 v4, v3, v4
	v_min_u32_e32 v166, 0x100, v4
	v_min_u32_e32 v167, 0x120, v4
	v_or_b32_e32 v4, 22, v114
	v_sub_u32_e32 v4, v3, v4
	v_min_u32_e32 v168, 0x100, v4
	v_min_u32_e32 v169, 0x120, v4
	v_or_b32_e32 v4, 23, v114
	v_ashrrev_i32_e32 v117, 31, v116
	v_sub_u32_e32 v3, v3, v4
	s_lshl_b32 s8, s16, 7
	v_min_u32_e32 v170, 0x100, v3
	v_min_u32_e32 v171, 0x120, v3
	v_and_b32_e32 v3, 7, v98
	v_lshlrev_b64 v[4:5], 11, v[116:117]
	s_and_b32 s8, s8, 0x80
	v_lshlrev_b32_e32 v0, 3, v98
	v_lshlrev_b32_e32 v122, 4, v3
	v_lshl_add_u64 v[124:125], s[12:13], 0, v[4:5]
	v_lshl_or_b32 v3, v112, 2, s8
	v_lshlrev_b32_e32 v4, 5, v6
	v_and_b32_e32 v0, 56, v0
	v_mul_u32_u24_e32 v137, 0x90, v2
	v_lshlrev_b32_e32 v2, 2, v6
	v_sub_u32_e32 v3, v3, v4
	v_lshlrev_b32_e32 v138, 4, v6
	v_mul_u32_u24_e32 v139, 0x90, v112
	v_mov_b32_e32 v123, v1
	v_add_u32_e32 v172, 0, v3
	v_lshlrev_b32_e32 v126, 1, v0
	v_lshlrev_b32_e32 v128, 1, v2
	v_readlane_b32 s19, v247, 2
	s_branch .LBB0_486

.LBB0_491:
	s_bitcmp1_b32 s9, 0
	s_cselect_b32 s14, 0x9000, 0
	s_add_i32 s30, s8, s26
	s_add_i32 s28, s14, 0
	s_add_i32 s29, s30, -2
	s_cmp_lt_i32 s29, s25
	s_cselect_b64 s[14:15], -1, 0
	s_cmp_gt_i32 s29, s23
	s_cselect_b64 s[34:35], -1, 0
	s_or_b64 s[14:15], s[14:15], s[34:35]
	s_and_b64 vcc, exec, s[14:15]
	s_cbranch_vccnz .LBB0_502
	s_add_i32 s31, s27, s26
	s_add_i32 s14, s31, -2
	s_cmp_lt_i32 s14, -3
	s_mov_b64 s[14:15], -1
	s_cbranch_scc0 .LBB0_499
	s_cmp_lg_u32 s31, -2
	s_cbranch_scc0 .LBB0_495
	v_mov_b32_e32 v0, s24
	ds_read_b128 v[48:51], v0 offset:2048
	ds_read_b128 v[52:55], v0 offset:2048
	ds_read_b128 v[56:59], v0 offset:2048
	ds_read_b128 v[60:63], v0 offset:2048
	ds_read_b128 v[64:67], v0 offset:2048
	ds_read_b128 v[68:71], v0 offset:2048
	ds_read_b128 v[72:75], v0 offset:2048
	ds_read_b128 v[76:79], v0 offset:2048
	s_mov_b64 s[14:15], 0
	s_branch .LBB0_496
.LBB0_495:
.LBB0_496:
	s_andn2_b64 vcc, exec, s[14:15]
	s_cbranch_vccnz .LBB0_498
	ds_read_b32 v48, v127 offset:1024
	ds_read_b32 v64, v129 offset:896
	ds_read_b32 v49, v173 offset:1024
	ds_read_b32 v65, v174 offset:896
	ds_read_b32 v50, v175 offset:1024
	ds_read_b32 v66, v176 offset:896
	ds_read_b32 v51, v177 offset:1024
	ds_read_b32 v67, v178 offset:896
	ds_read_b32 v52, v179 offset:1024
	ds_read_b32 v68, v180 offset:896
	ds_read_b32 v53, v181 offset:1024
	ds_read_b32 v69, v182 offset:896
	ds_read_b32 v54, v183 offset:1024
	ds_read_b32 v70, v184 offset:896
	ds_read_b32 v55, v185 offset:1024
	ds_read_b32 v71, v186 offset:896
	ds_read_b32 v56, v187 offset:1024
	ds_read_b32 v72, v188 offset:896
	ds_read_b32 v57, v189 offset:1024
	ds_read_b32 v73, v190 offset:896
	ds_read_b32 v58, v191 offset:1024
	ds_read_b32 v74, v192 offset:896
	ds_read_b32 v59, v193 offset:1024
	ds_read_b32 v75, v194 offset:896
	ds_read_b32 v60, v195 offset:1024
	ds_read_b32 v76, v196 offset:896
	ds_read_b32 v61, v197 offset:1024
	ds_read_b32 v77, v198 offset:896
	ds_read_b32 v62, v199 offset:1024
	ds_read_b32 v78, v200 offset:896
	ds_read_b32 v63, v201 offset:1024
	ds_read_b32 v79, v212 offset:896

.LBB0_502:
	s_add_i32 s30, s30, -1
	s_cmp_lt_i32 s30, s25
	s_cselect_b64 s[14:15], -1, 0
	s_cmp_ge_i32 s29, s23
	s_cselect_b64 s[30:31], -1, 0
	s_or_b64 s[14:15], s[30:31], s[14:15]
	s_and_b64 vcc, exec, s[14:15]
	s_cbranch_vccnz .LBB0_513
	s_add_i32 s29, s27, s26
	s_add_i32 s14, s29, -1
	s_cmp_lt_i32 s14, -3
	s_mov_b64 s[14:15], -1
	s_cbranch_scc0 .LBB0_510
	s_cmp_lg_u32 s29, -3
	s_cbranch_scc0 .LBB0_506
	v_mov_b32_e32 v0, s24
	ds_read_b128 v[48:51], v0 offset:2048
	ds_read_b128 v[52:55], v0 offset:2048
	ds_read_b128 v[56:59], v0 offset:2048
	ds_read_b128 v[60:63], v0 offset:2048
	ds_read_b128 v[64:67], v0 offset:2048
	ds_read_b128 v[68:71], v0 offset:2048
	ds_read_b128 v[72:75], v0 offset:2048
	ds_read_b128 v[76:79], v0 offset:2048
	s_mov_b64 s[14:15], 0
	s_branch .LBB0_507
.LBB0_506:
.LBB0_507:
	s_andn2_b64 vcc, exec, s[14:15]
	s_cbranch_vccnz .LBB0_509
	ds_read_b32 v64, v127 offset:1024
	ds_read_b32 v48, v129 offset:896
	ds_read_b32 v65, v173 offset:1024
	ds_read_b32 v49, v174 offset:896
	ds_read_b32 v66, v175 offset:1024
	ds_read_b32 v50, v176 offset:896
	ds_read_b32 v67, v177 offset:1024
	ds_read_b32 v51, v178 offset:896
	ds_read_b32 v68, v179 offset:1024
	ds_read_b32 v52, v180 offset:896
	ds_read_b32 v69, v181 offset:1024
	ds_read_b32 v53, v182 offset:896
	ds_read_b32 v70, v183 offset:1024
	ds_read_b32 v54, v184 offset:896
	ds_read_b32 v71, v185 offset:1024
	ds_read_b32 v55, v186 offset:896
	ds_read_b32 v72, v187 offset:1024
	ds_read_b32 v56, v188 offset:896
	ds_read_b32 v73, v189 offset:1024
	ds_read_b32 v57, v190 offset:896
	ds_read_b32 v74, v191 offset:1024
	ds_read_b32 v58, v192 offset:896
	ds_read_b32 v75, v193 offset:1024
	ds_read_b32 v59, v194 offset:896
	ds_read_b32 v76, v195 offset:1024
	ds_read_b32 v60, v196 offset:896
	ds_read_b32 v77, v197 offset:1024
	ds_read_b32 v61, v198 offset:896
	ds_read_b32 v78, v199 offset:1024
	ds_read_b32 v62, v200 offset:896
	ds_read_b32 v79, v201 offset:1024
	ds_read_b32 v63, v212 offset:896
